# v46 + non-first units skip the accumulator zeroing: the peeled copy's first MFMA per accumulator takes C=0
# speedup vs baseline: 1.0040x; 1.0040x over previous
.LBB0_393:
	s_ashr_i32 s19, s18, 31
	s_lshl_b64 s[0:1], s[18:19], 20
	s_add_u32 s20, s42, s0
	s_addc_u32 s21, s43, s1
	s_and_b64 s[0:1], s[4:5], exec
	s_cselect_b32 s7, s21, s25
	s_cselect_b32 s19, s20, s24
	s_ashr_i32 s17, s16, 31
	s_lshl_b64 s[0:1], s[16:17], 20
	s_add_u32 s22, s30, s0
	s_addc_u32 s23, s31, s1
	s_and_b64 s[0:1], s[4:5], exec
	s_cselect_b32 s17, s23, s27
	s_cselect_b32 s49, s22, s26
	s_add_u32 s24, s24, 0x80080
	s_addc_u32 s25, s25, 0
	s_add_u32 s58, s26, 0x100
	v_mov_b32_e32 v2, 0
	s_addc_u32 s59, s27, 0
	s_mov_b32 s60, -2
	v_mov_b32_e32 v3, v2
	s_waitcnt lgkmcnt(0)
	s_cmp_eq_u32 s101, 0x80000001
	s_cbranch_scc0 .Lpeel_zero_0
	s_add_u32 s0, s24, 0xfff80080
	s_addc_u32 s1, s25, -1
	s_add_i32 s33, 0, 0x10000
	s_cmp_eq_u32 s60, 28
	s_cselect_b32 s29, s7, s1
	s_cselect_b32 s28, s19, s0
	s_cselect_b32 s27, s17, s59
	s_cselect_b32 s26, s49, s58
	s_add_i32 s55, 0, 0x14000
	ds_read_b128 v[142:145], v151
	ds_read_b128 v[146:149], v151 offset:1024
	ds_read_b128 v[154:157], v151 offset:2048
	ds_read_b128 v[158:161], v151 offset:3072
	ds_read_b128 v[162:165], v151 offset:16384
	ds_read_b128 v[166:169], v151 offset:17408
	ds_read_b128 v[170:173], v151 offset:18432
	ds_read_b128 v[174:177], v151 offset:19456
	s_add_i32 m0, s9, 0xc000
	ds_read_b128 v[178:181], v153
	ds_read_b128 v[182:185], v153 offset:1024
	ds_read_b128 v[186:189], v153 offset:2048
	ds_read_b128 v[190:193], v153 offset:3072
	ds_read_b128 v[194:197], v153 offset:4096
	ds_read_b128 v[198:201], v153 offset:5120
	ds_read_b128 v[208:211], v153 offset:6144
	ds_read_b128 v[212:215], v153 offset:7168
	global_load_lds_dwordx4 v138, s[24:25]
	s_add_i32 m0, s9, 0xe000
	s_nop 0
	global_load_lds_dwordx4 v140, s[24:25]
	s_waitcnt vmcnt(24)
	s_waitcnt lgkmcnt(0)
	s_setprio 1
	s_barrier
	v_mfma_f32_16x16x32_bf16 v[126:129], v[142:145], v[178:181], 0
	v_mfma_f32_16x16x32_bf16 v[122:125], v[154:157], v[178:181], 0
	v_mfma_f32_16x16x32_bf16 v[110:113], v[142:145], v[186:189], 0
	v_mfma_f32_16x16x32_bf16 v[106:109], v[154:157], v[186:189], 0
	v_mfma_f32_16x16x32_bf16 v[94:97], v[142:145], v[194:197], 0
	v_mfma_f32_16x16x32_bf16 v[90:93], v[154:157], v[194:197], 0
	v_mfma_f32_16x16x32_bf16 v[78:81], v[142:145], v[208:211], 0
	v_mfma_f32_16x16x32_bf16 v[74:77], v[154:157], v[208:211], 0
	v_mfma_f32_16x16x32_bf16 v[126:129], v[146:149], v[182:185], v[126:129]
	v_mfma_f32_16x16x32_bf16 v[122:125], v[158:161], v[182:185], v[122:125]
	v_mfma_f32_16x16x32_bf16 v[110:113], v[146:149], v[190:193], v[110:113]
	v_mfma_f32_16x16x32_bf16 v[106:109], v[158:161], v[190:193], v[106:109]
	v_mfma_f32_16x16x32_bf16 v[94:97], v[146:149], v[198:201], v[94:97]
	v_mfma_f32_16x16x32_bf16 v[90:93], v[158:161], v[198:201], v[90:93]
	v_mfma_f32_16x16x32_bf16 v[78:81], v[146:149], v[212:215], v[78:81]
	v_mfma_f32_16x16x32_bf16 v[74:77], v[158:161], v[212:215], v[74:77]
	v_mfma_f32_16x16x32_bf16 v[118:121], v[162:165], v[178:181], 0
	v_mfma_f32_16x16x32_bf16 v[114:117], v[170:173], v[178:181], 0
	v_mfma_f32_16x16x32_bf16 v[102:105], v[162:165], v[186:189], 0
	v_mfma_f32_16x16x32_bf16 v[98:101], v[170:173], v[186:189], 0
	v_mfma_f32_16x16x32_bf16 v[86:89], v[162:165], v[194:197], 0
	v_mfma_f32_16x16x32_bf16 v[82:85], v[170:173], v[194:197], 0
	v_mfma_f32_16x16x32_bf16 v[70:73], v[162:165], v[208:211], 0
	v_mfma_f32_16x16x32_bf16 v[66:69], v[170:173], v[208:211], 0
	v_mfma_f32_16x16x32_bf16 v[118:121], v[166:169], v[182:185], v[118:121]
	v_mfma_f32_16x16x32_bf16 v[114:117], v[174:177], v[182:185], v[114:117]
	v_mfma_f32_16x16x32_bf16 v[102:105], v[166:169], v[190:193], v[102:105]
	v_mfma_f32_16x16x32_bf16 v[98:101], v[174:177], v[190:193], v[98:101]
	v_mfma_f32_16x16x32_bf16 v[86:89], v[166:169], v[198:201], v[86:89]
	v_mfma_f32_16x16x32_bf16 v[82:85], v[174:177], v[198:201], v[82:85]
	v_mfma_f32_16x16x32_bf16 v[70:73], v[166:169], v[212:215], v[70:73]
	v_mfma_f32_16x16x32_bf16 v[66:69], v[174:177], v[212:215], v[66:69]
	s_barrier
	s_setprio 0
	s_add_i32 s0, s33, s34
	s_mov_b32 m0, s0
	ds_read_b128 v[178:181], v153 offset:16384
	ds_read_b128 v[182:185], v153 offset:17408
	ds_read_b128 v[186:189], v153 offset:18432
	ds_read_b128 v[190:193], v153 offset:19456
	ds_read_b128 v[194:197], v153 offset:20480
	ds_read_b128 v[198:201], v153 offset:21504
	ds_read_b128 v[208:211], v153 offset:22528
	ds_read_b128 v[212:215], v153 offset:23552
	global_load_lds_dwordx4 v132, s[26:27]
	s_add_i32 m0, s0, 0x2000
	s_add_u32 s0, s26, 0x80000
	s_addc_u32 s1, s27, 0
	s_add_i32 s33, s55, s34
	global_load_lds_dwordx4 v136, s[26:27]
	s_mov_b32 m0, s33
	s_nop 0
	global_load_lds_dwordx4 v132, s[0:1]
	s_add_i32 m0, s33, 0x2000
	s_nop 0
	global_load_lds_dwordx4 v136, s[0:1]
	s_mov_b32 m0, s9
	s_nop 0
	global_load_lds_dwordx4 v130, s[28:29]
	s_mov_b32 m0, s35
	s_nop 0
	global_load_lds_dwordx4 v134, s[28:29]
	s_waitcnt vmcnt(24)
	s_waitcnt lgkmcnt(0)
	s_setprio 1
	s_barrier
	v_mfma_f32_16x16x32_bf16 v[62:65], v[142:145], v[178:181], 0
	v_mfma_f32_16x16x32_bf16 v[58:61], v[154:157], v[178:181], 0
	v_mfma_f32_16x16x32_bf16 v[46:49], v[142:145], v[186:189], 0
	v_mfma_f32_16x16x32_bf16 v[42:45], v[154:157], v[186:189], 0
	v_mfma_f32_16x16x32_bf16 v[30:33], v[142:145], v[194:197], 0
	v_mfma_f32_16x16x32_bf16 v[26:29], v[154:157], v[194:197], 0
	v_mfma_f32_16x16x32_bf16 v[14:17], v[142:145], v[208:211], 0
	v_mfma_f32_16x16x32_bf16 v[10:13], v[154:157], v[208:211], 0
	v_mfma_f32_16x16x32_bf16 v[62:65], v[146:149], v[182:185], v[62:65]
	v_mfma_f32_16x16x32_bf16 v[58:61], v[158:161], v[182:185], v[58:61]
	v_mfma_f32_16x16x32_bf16 v[46:49], v[146:149], v[190:193], v[46:49]
	v_mfma_f32_16x16x32_bf16 v[42:45], v[158:161], v[190:193], v[42:45]
	v_mfma_f32_16x16x32_bf16 v[30:33], v[146:149], v[198:201], v[30:33]
	v_mfma_f32_16x16x32_bf16 v[26:29], v[158:161], v[198:201], v[26:29]
	v_mfma_f32_16x16x32_bf16 v[14:17], v[146:149], v[212:215], v[14:17]
	v_mfma_f32_16x16x32_bf16 v[10:13], v[158:161], v[212:215], v[10:13]
	v_mfma_f32_16x16x32_bf16 v[54:57], v[162:165], v[178:181], 0
	v_mfma_f32_16x16x32_bf16 v[50:53], v[170:173], v[178:181], 0
	v_mfma_f32_16x16x32_bf16 v[38:41], v[162:165], v[186:189], 0
	v_mfma_f32_16x16x32_bf16 v[34:37], v[170:173], v[186:189], 0
	v_mfma_f32_16x16x32_bf16 v[22:25], v[162:165], v[194:197], 0
	v_mfma_f32_16x16x32_bf16 v[18:21], v[170:173], v[194:197], 0
	v_mfma_f32_16x16x32_bf16 v[6:9], v[162:165], v[208:211], 0
	v_mfma_f32_16x16x32_bf16 v[2:5], v[170:173], v[208:211], 0
	v_mfma_f32_16x16x32_bf16 v[54:57], v[166:169], v[182:185], v[54:57]
	v_mfma_f32_16x16x32_bf16 v[50:53], v[174:177], v[182:185], v[50:53]
	v_mfma_f32_16x16x32_bf16 v[38:41], v[166:169], v[190:193], v[38:41]
	v_mfma_f32_16x16x32_bf16 v[34:37], v[174:177], v[190:193], v[34:37]
	v_mfma_f32_16x16x32_bf16 v[22:25], v[166:169], v[198:201], v[22:25]
	v_mfma_f32_16x16x32_bf16 v[18:21], v[174:177], v[198:201], v[18:21]
	v_mfma_f32_16x16x32_bf16 v[6:9], v[166:169], v[212:215], v[6:9]
	v_mfma_f32_16x16x32_bf16 v[2:5], v[174:177], v[212:215], v[2:5]
	s_barrier
	s_setprio 0
	s_branch .Lpeel_mid_0
.Lpeel_zero_0:
	v_pk_mov_b32 v[4:5], v[2:3], v[2:3] op_sel:[0,1]
	v_pk_mov_b32 v[6:7], v[2:3], v[2:3] op_sel:[0,1]
	v_pk_mov_b32 v[8:9], v[2:3], v[2:3] op_sel:[0,1]
	v_pk_mov_b32 v[18:19], v[2:3], v[2:3] op_sel:[0,1]
	v_pk_mov_b32 v[20:21], v[2:3], v[2:3] op_sel:[0,1]
	v_pk_mov_b32 v[22:23], v[2:3], v[2:3] op_sel:[0,1]
	v_pk_mov_b32 v[24:25], v[2:3], v[2:3] op_sel:[0,1]
	v_pk_mov_b32 v[34:35], v[2:3], v[2:3] op_sel:[0,1]
	v_pk_mov_b32 v[36:37], v[2:3], v[2:3] op_sel:[0,1]
	v_pk_mov_b32 v[38:39], v[2:3], v[2:3] op_sel:[0,1]
	v_pk_mov_b32 v[40:41], v[2:3], v[2:3] op_sel:[0,1]
	v_pk_mov_b32 v[50:51], v[2:3], v[2:3] op_sel:[0,1]
	v_pk_mov_b32 v[52:53], v[2:3], v[2:3] op_sel:[0,1]
	v_pk_mov_b32 v[54:55], v[2:3], v[2:3] op_sel:[0,1]
	v_pk_mov_b32 v[56:57], v[2:3], v[2:3] op_sel:[0,1]
	v_pk_mov_b32 v[10:11], v[2:3], v[2:3] op_sel:[0,1]
	v_pk_mov_b32 v[12:13], v[2:3], v[2:3] op_sel:[0,1]
	v_pk_mov_b32 v[14:15], v[2:3], v[2:3] op_sel:[0,1]
	v_pk_mov_b32 v[16:17], v[2:3], v[2:3] op_sel:[0,1]
	v_pk_mov_b32 v[26:27], v[2:3], v[2:3] op_sel:[0,1]
	v_pk_mov_b32 v[28:29], v[2:3], v[2:3] op_sel:[0,1]
	v_pk_mov_b32 v[30:31], v[2:3], v[2:3] op_sel:[0,1]
	v_pk_mov_b32 v[32:33], v[2:3], v[2:3] op_sel:[0,1]
	v_pk_mov_b32 v[42:43], v[2:3], v[2:3] op_sel:[0,1]
	v_pk_mov_b32 v[44:45], v[2:3], v[2:3] op_sel:[0,1]
	v_pk_mov_b32 v[46:47], v[2:3], v[2:3] op_sel:[0,1]
	v_pk_mov_b32 v[48:49], v[2:3], v[2:3] op_sel:[0,1]
	v_pk_mov_b32 v[58:59], v[2:3], v[2:3] op_sel:[0,1]
	v_pk_mov_b32 v[60:61], v[2:3], v[2:3] op_sel:[0,1]
	v_pk_mov_b32 v[62:63], v[2:3], v[2:3] op_sel:[0,1]
	v_pk_mov_b32 v[64:65], v[2:3], v[2:3] op_sel:[0,1]
	v_pk_mov_b32 v[66:67], v[2:3], v[2:3] op_sel:[0,1]
	v_pk_mov_b32 v[68:69], v[2:3], v[2:3] op_sel:[0,1]
	v_pk_mov_b32 v[70:71], v[2:3], v[2:3] op_sel:[0,1]
	v_pk_mov_b32 v[72:73], v[2:3], v[2:3] op_sel:[0,1]
	v_pk_mov_b32 v[82:83], v[2:3], v[2:3] op_sel:[0,1]
	v_pk_mov_b32 v[84:85], v[2:3], v[2:3] op_sel:[0,1]
	v_pk_mov_b32 v[86:87], v[2:3], v[2:3] op_sel:[0,1]
	v_pk_mov_b32 v[88:89], v[2:3], v[2:3] op_sel:[0,1]
	v_pk_mov_b32 v[98:99], v[2:3], v[2:3] op_sel:[0,1]
	v_pk_mov_b32 v[100:101], v[2:3], v[2:3] op_sel:[0,1]
	v_pk_mov_b32 v[102:103], v[2:3], v[2:3] op_sel:[0,1]
	v_pk_mov_b32 v[104:105], v[2:3], v[2:3] op_sel:[0,1]
	v_pk_mov_b32 v[114:115], v[2:3], v[2:3] op_sel:[0,1]
	v_pk_mov_b32 v[116:117], v[2:3], v[2:3] op_sel:[0,1]
	v_pk_mov_b32 v[118:119], v[2:3], v[2:3] op_sel:[0,1]
	v_pk_mov_b32 v[120:121], v[2:3], v[2:3] op_sel:[0,1]
	v_pk_mov_b32 v[74:75], v[2:3], v[2:3] op_sel:[0,1]
	v_pk_mov_b32 v[76:77], v[2:3], v[2:3] op_sel:[0,1]
	v_pk_mov_b32 v[78:79], v[2:3], v[2:3] op_sel:[0,1]
	v_pk_mov_b32 v[80:81], v[2:3], v[2:3] op_sel:[0,1]
	v_pk_mov_b32 v[90:91], v[2:3], v[2:3] op_sel:[0,1]
	v_pk_mov_b32 v[92:93], v[2:3], v[2:3] op_sel:[0,1]
	v_pk_mov_b32 v[94:95], v[2:3], v[2:3] op_sel:[0,1]
	v_pk_mov_b32 v[96:97], v[2:3], v[2:3] op_sel:[0,1]
	v_pk_mov_b32 v[106:107], v[2:3], v[2:3] op_sel:[0,1]
	v_pk_mov_b32 v[108:109], v[2:3], v[2:3] op_sel:[0,1]
	v_pk_mov_b32 v[110:111], v[2:3], v[2:3] op_sel:[0,1]
	v_pk_mov_b32 v[112:113], v[2:3], v[2:3] op_sel:[0,1]
	v_pk_mov_b32 v[122:123], v[2:3], v[2:3] op_sel:[0,1]
	v_pk_mov_b32 v[124:125], v[2:3], v[2:3] op_sel:[0,1]
	v_pk_mov_b32 v[126:127], v[2:3], v[2:3] op_sel:[0,1]
	v_pk_mov_b32 v[128:129], v[2:3], v[2:3] op_sel:[0,1]

.LBB0_836:
	s_ashr_i32 s11, s10, 31
	s_lshl_b64 s[0:1], s[10:11], 20
	s_add_u32 s14, s42, s0
	s_addc_u32 s15, s43, s1
	s_and_b64 s[0:1], s[2:3], exec
	s_cselect_b32 s11, s15, s19
	s_cselect_b32 s38, s14, s18
	s_ashr_i32 s9, s8, 31
	s_lshl_b64 s[0:1], s[8:9], 20
	s_add_u32 s16, s24, s0
	s_addc_u32 s17, s25, s1
	s_and_b64 s[0:1], s[2:3], exec
	s_cselect_b32 s9, s17, s21
	s_cselect_b32 s39, s16, s20
	s_add_u32 s18, s18, 0x80080
	s_addc_u32 s19, s19, 0
	s_add_u32 s49, s20, 0x100
	v_mov_b32_e32 v2, 0
	s_addc_u32 s58, s21, 0
	s_mov_b32 s59, -2
	v_mov_b32_e32 v3, v2
	s_cmp_eq_u32 s101, 0x80000001
	s_cbranch_scc0 .Lpeel_zero_3
	s_add_u32 s0, s18, 0xfff80080
	s_addc_u32 s1, s19, -1
	s_add_i32 s33, 0, 0x10000
	s_cmp_eq_u32 s59, 28
	s_cselect_b32 s23, s11, s1
	s_cselect_b32 s22, s38, s0
	s_cselect_b32 s21, s9, s58
	s_cselect_b32 s20, s39, s49
	s_add_i32 s55, 0, 0x14000
	ds_read_b128 v[146:149], v143
	ds_read_b128 v[150:153], v143 offset:1024
	ds_read_b128 v[154:157], v143 offset:2048
	ds_read_b128 v[158:161], v143 offset:3072
	ds_read_b128 v[162:165], v143 offset:16384
	ds_read_b128 v[166:169], v143 offset:17408
	ds_read_b128 v[170:173], v143 offset:18432
	ds_read_b128 v[174:177], v143 offset:19456
	s_add_i32 m0, s27, 0xc000
	ds_read_b128 v[178:181], v145
	ds_read_b128 v[182:185], v145 offset:1024
	ds_read_b128 v[186:189], v145 offset:2048
	ds_read_b128 v[190:193], v145 offset:3072
	ds_read_b128 v[194:197], v145 offset:4096
	ds_read_b128 v[198:201], v145 offset:5120
	ds_read_b128 v[208:211], v145 offset:6144
	ds_read_b128 v[212:215], v145 offset:7168
	global_load_lds_dwordx4 v136, s[18:19]
	s_add_i32 m0, s27, 0xe000
	s_nop 0
	global_load_lds_dwordx4 v138, s[18:19]
	s_waitcnt vmcnt(16)
	s_waitcnt lgkmcnt(0)
	s_setprio 1
	s_barrier
	v_mfma_f32_16x16x32_bf16 v[126:129], v[146:149], v[178:181], 0
	v_mfma_f32_16x16x32_bf16 v[118:121], v[154:157], v[178:181], 0
	v_mfma_f32_16x16x32_bf16 v[110:113], v[146:149], v[186:189], 0
	v_mfma_f32_16x16x32_bf16 v[102:105], v[154:157], v[186:189], 0
	v_mfma_f32_16x16x32_bf16 v[94:97], v[146:149], v[194:197], 0
	v_mfma_f32_16x16x32_bf16 v[86:89], v[154:157], v[194:197], 0
	v_mfma_f32_16x16x32_bf16 v[78:81], v[146:149], v[208:211], 0
	v_mfma_f32_16x16x32_bf16 v[70:73], v[154:157], v[208:211], 0
	v_mfma_f32_16x16x32_bf16 v[126:129], v[150:153], v[182:185], v[126:129]
	v_mfma_f32_16x16x32_bf16 v[118:121], v[158:161], v[182:185], v[118:121]
	v_mfma_f32_16x16x32_bf16 v[110:113], v[150:153], v[190:193], v[110:113]
	v_mfma_f32_16x16x32_bf16 v[102:105], v[158:161], v[190:193], v[102:105]
	v_mfma_f32_16x16x32_bf16 v[94:97], v[150:153], v[198:201], v[94:97]
	v_mfma_f32_16x16x32_bf16 v[86:89], v[158:161], v[198:201], v[86:89]
	v_mfma_f32_16x16x32_bf16 v[78:81], v[150:153], v[212:215], v[78:81]
	v_mfma_f32_16x16x32_bf16 v[70:73], v[158:161], v[212:215], v[70:73]
	v_mfma_f32_16x16x32_bf16 v[122:125], v[162:165], v[178:181], 0
	v_mfma_f32_16x16x32_bf16 v[114:117], v[170:173], v[178:181], 0
	v_mfma_f32_16x16x32_bf16 v[106:109], v[162:165], v[186:189], 0
	v_mfma_f32_16x16x32_bf16 v[98:101], v[170:173], v[186:189], 0
	v_mfma_f32_16x16x32_bf16 v[90:93], v[162:165], v[194:197], 0
	v_mfma_f32_16x16x32_bf16 v[82:85], v[170:173], v[194:197], 0
	v_mfma_f32_16x16x32_bf16 v[74:77], v[162:165], v[208:211], 0
	v_mfma_f32_16x16x32_bf16 v[66:69], v[170:173], v[208:211], 0
	v_mfma_f32_16x16x32_bf16 v[122:125], v[166:169], v[182:185], v[122:125]
	v_mfma_f32_16x16x32_bf16 v[114:117], v[174:177], v[182:185], v[114:117]
	v_mfma_f32_16x16x32_bf16 v[106:109], v[166:169], v[190:193], v[106:109]
	v_mfma_f32_16x16x32_bf16 v[98:101], v[174:177], v[190:193], v[98:101]
	v_mfma_f32_16x16x32_bf16 v[90:93], v[166:169], v[198:201], v[90:93]
	v_mfma_f32_16x16x32_bf16 v[82:85], v[174:177], v[198:201], v[82:85]
	v_mfma_f32_16x16x32_bf16 v[74:77], v[166:169], v[212:215], v[74:77]
	v_mfma_f32_16x16x32_bf16 v[66:69], v[174:177], v[212:215], v[66:69]
	s_barrier
	s_setprio 0
	s_add_i32 s0, s33, s26
	s_mov_b32 m0, s0
	ds_read_b128 v[178:181], v145 offset:16384
	ds_read_b128 v[182:185], v145 offset:17408
	ds_read_b128 v[186:189], v145 offset:18432
	ds_read_b128 v[190:193], v145 offset:19456
	ds_read_b128 v[194:197], v145 offset:20480
	ds_read_b128 v[198:201], v145 offset:21504
	ds_read_b128 v[208:211], v145 offset:22528
	ds_read_b128 v[212:215], v145 offset:23552
	global_load_lds_dwordx4 v202, s[20:21]
	s_add_i32 m0, s0, 0x2000
	s_add_u32 s0, s20, 0x80000
	s_addc_u32 s1, s21, 0
	s_add_i32 s33, s55, s26
	global_load_lds_dwordx4 v130, s[20:21]
	s_mov_b32 m0, s33
	s_nop 0
	global_load_lds_dwordx4 v202, s[0:1]
	s_add_i32 m0, s33, 0x2000
	s_nop 0
	global_load_lds_dwordx4 v130, s[0:1]
	s_mov_b32 m0, s27
	s_nop 0
	global_load_lds_dwordx4 v134, s[22:23]
	s_mov_b32 m0, s28
	s_nop 0
	global_load_lds_dwordx4 v132, s[22:23]
	s_waitcnt vmcnt(16)
	s_waitcnt lgkmcnt(0)
	s_setprio 1
	s_barrier
	v_mfma_f32_16x16x32_bf16 v[62:65], v[146:149], v[178:181], 0
	v_mfma_f32_16x16x32_bf16 v[54:57], v[154:157], v[178:181], 0
	v_mfma_f32_16x16x32_bf16 v[46:49], v[146:149], v[186:189], 0
	v_mfma_f32_16x16x32_bf16 v[38:41], v[154:157], v[186:189], 0
	v_mfma_f32_16x16x32_bf16 v[30:33], v[146:149], v[194:197], 0
	v_mfma_f32_16x16x32_bf16 v[22:25], v[154:157], v[194:197], 0
	v_mfma_f32_16x16x32_bf16 v[14:17], v[146:149], v[208:211], 0
	v_mfma_f32_16x16x32_bf16 v[6:9], v[154:157], v[208:211], 0
	v_mfma_f32_16x16x32_bf16 v[62:65], v[150:153], v[182:185], v[62:65]
	v_mfma_f32_16x16x32_bf16 v[54:57], v[158:161], v[182:185], v[54:57]
	v_mfma_f32_16x16x32_bf16 v[46:49], v[150:153], v[190:193], v[46:49]
	v_mfma_f32_16x16x32_bf16 v[38:41], v[158:161], v[190:193], v[38:41]
	v_mfma_f32_16x16x32_bf16 v[30:33], v[150:153], v[198:201], v[30:33]
	v_mfma_f32_16x16x32_bf16 v[22:25], v[158:161], v[198:201], v[22:25]
	v_mfma_f32_16x16x32_bf16 v[14:17], v[150:153], v[212:215], v[14:17]
	v_mfma_f32_16x16x32_bf16 v[6:9], v[158:161], v[212:215], v[6:9]
	v_mfma_f32_16x16x32_bf16 v[58:61], v[162:165], v[178:181], 0
	v_mfma_f32_16x16x32_bf16 v[50:53], v[170:173], v[178:181], 0
	v_mfma_f32_16x16x32_bf16 v[42:45], v[162:165], v[186:189], 0
	v_mfma_f32_16x16x32_bf16 v[34:37], v[170:173], v[186:189], 0
	v_mfma_f32_16x16x32_bf16 v[26:29], v[162:165], v[194:197], 0
	v_mfma_f32_16x16x32_bf16 v[18:21], v[170:173], v[194:197], 0
	v_mfma_f32_16x16x32_bf16 v[10:13], v[162:165], v[208:211], 0
	v_mfma_f32_16x16x32_bf16 v[2:5], v[170:173], v[208:211], 0
	v_mfma_f32_16x16x32_bf16 v[58:61], v[166:169], v[182:185], v[58:61]
	v_mfma_f32_16x16x32_bf16 v[50:53], v[174:177], v[182:185], v[50:53]
	v_mfma_f32_16x16x32_bf16 v[42:45], v[166:169], v[190:193], v[42:45]
	v_mfma_f32_16x16x32_bf16 v[34:37], v[174:177], v[190:193], v[34:37]
	v_mfma_f32_16x16x32_bf16 v[26:29], v[166:169], v[198:201], v[26:29]
	v_mfma_f32_16x16x32_bf16 v[18:21], v[174:177], v[198:201], v[18:21]
	v_mfma_f32_16x16x32_bf16 v[10:13], v[166:169], v[212:215], v[10:13]
	v_mfma_f32_16x16x32_bf16 v[2:5], v[174:177], v[212:215], v[2:5]
	s_barrier
	s_setprio 0
	s_branch .Lpeel_mid_3
.Lpeel_zero_3:
	v_pk_mov_b32 v[4:5], v[2:3], v[2:3] op_sel:[0,1]
	v_pk_mov_b32 v[10:11], v[2:3], v[2:3] op_sel:[0,1]
	v_pk_mov_b32 v[12:13], v[2:3], v[2:3] op_sel:[0,1]
	v_pk_mov_b32 v[18:19], v[2:3], v[2:3] op_sel:[0,1]
	v_pk_mov_b32 v[20:21], v[2:3], v[2:3] op_sel:[0,1]
	v_pk_mov_b32 v[26:27], v[2:3], v[2:3] op_sel:[0,1]
	v_pk_mov_b32 v[28:29], v[2:3], v[2:3] op_sel:[0,1]
	v_pk_mov_b32 v[34:35], v[2:3], v[2:3] op_sel:[0,1]
	v_pk_mov_b32 v[36:37], v[2:3], v[2:3] op_sel:[0,1]
	v_pk_mov_b32 v[42:43], v[2:3], v[2:3] op_sel:[0,1]
	v_pk_mov_b32 v[44:45], v[2:3], v[2:3] op_sel:[0,1]
	v_pk_mov_b32 v[50:51], v[2:3], v[2:3] op_sel:[0,1]
	v_pk_mov_b32 v[52:53], v[2:3], v[2:3] op_sel:[0,1]
	v_pk_mov_b32 v[58:59], v[2:3], v[2:3] op_sel:[0,1]
	v_pk_mov_b32 v[60:61], v[2:3], v[2:3] op_sel:[0,1]
	v_pk_mov_b32 v[6:7], v[2:3], v[2:3] op_sel:[0,1]
	v_pk_mov_b32 v[8:9], v[2:3], v[2:3] op_sel:[0,1]
	v_pk_mov_b32 v[14:15], v[2:3], v[2:3] op_sel:[0,1]
	v_pk_mov_b32 v[16:17], v[2:3], v[2:3] op_sel:[0,1]
	v_pk_mov_b32 v[22:23], v[2:3], v[2:3] op_sel:[0,1]
	v_pk_mov_b32 v[24:25], v[2:3], v[2:3] op_sel:[0,1]
	v_pk_mov_b32 v[30:31], v[2:3], v[2:3] op_sel:[0,1]
	v_pk_mov_b32 v[32:33], v[2:3], v[2:3] op_sel:[0,1]
	v_pk_mov_b32 v[38:39], v[2:3], v[2:3] op_sel:[0,1]
	v_pk_mov_b32 v[40:41], v[2:3], v[2:3] op_sel:[0,1]
	v_pk_mov_b32 v[46:47], v[2:3], v[2:3] op_sel:[0,1]
	v_pk_mov_b32 v[48:49], v[2:3], v[2:3] op_sel:[0,1]
	v_pk_mov_b32 v[54:55], v[2:3], v[2:3] op_sel:[0,1]
	v_pk_mov_b32 v[56:57], v[2:3], v[2:3] op_sel:[0,1]
	v_pk_mov_b32 v[62:63], v[2:3], v[2:3] op_sel:[0,1]
	v_pk_mov_b32 v[64:65], v[2:3], v[2:3] op_sel:[0,1]
	v_pk_mov_b32 v[66:67], v[2:3], v[2:3] op_sel:[0,1]
	v_pk_mov_b32 v[68:69], v[2:3], v[2:3] op_sel:[0,1]
	v_pk_mov_b32 v[74:75], v[2:3], v[2:3] op_sel:[0,1]
	v_pk_mov_b32 v[76:77], v[2:3], v[2:3] op_sel:[0,1]
	v_pk_mov_b32 v[82:83], v[2:3], v[2:3] op_sel:[0,1]
	v_pk_mov_b32 v[84:85], v[2:3], v[2:3] op_sel:[0,1]
	v_pk_mov_b32 v[90:91], v[2:3], v[2:3] op_sel:[0,1]
	v_pk_mov_b32 v[92:93], v[2:3], v[2:3] op_sel:[0,1]
	v_pk_mov_b32 v[98:99], v[2:3], v[2:3] op_sel:[0,1]
	v_pk_mov_b32 v[100:101], v[2:3], v[2:3] op_sel:[0,1]
	v_pk_mov_b32 v[106:107], v[2:3], v[2:3] op_sel:[0,1]
	v_pk_mov_b32 v[108:109], v[2:3], v[2:3] op_sel:[0,1]
	v_pk_mov_b32 v[114:115], v[2:3], v[2:3] op_sel:[0,1]
	v_pk_mov_b32 v[116:117], v[2:3], v[2:3] op_sel:[0,1]
	v_pk_mov_b32 v[122:123], v[2:3], v[2:3] op_sel:[0,1]
	v_pk_mov_b32 v[124:125], v[2:3], v[2:3] op_sel:[0,1]
	v_pk_mov_b32 v[70:71], v[2:3], v[2:3] op_sel:[0,1]
	v_pk_mov_b32 v[72:73], v[2:3], v[2:3] op_sel:[0,1]
	v_pk_mov_b32 v[78:79], v[2:3], v[2:3] op_sel:[0,1]
	v_pk_mov_b32 v[80:81], v[2:3], v[2:3] op_sel:[0,1]
	v_pk_mov_b32 v[86:87], v[2:3], v[2:3] op_sel:[0,1]
	v_pk_mov_b32 v[88:89], v[2:3], v[2:3] op_sel:[0,1]
	v_pk_mov_b32 v[94:95], v[2:3], v[2:3] op_sel:[0,1]
	v_pk_mov_b32 v[96:97], v[2:3], v[2:3] op_sel:[0,1]
	v_pk_mov_b32 v[102:103], v[2:3], v[2:3] op_sel:[0,1]
	v_pk_mov_b32 v[104:105], v[2:3], v[2:3] op_sel:[0,1]
	v_pk_mov_b32 v[110:111], v[2:3], v[2:3] op_sel:[0,1]
	v_pk_mov_b32 v[112:113], v[2:3], v[2:3] op_sel:[0,1]
	v_pk_mov_b32 v[118:119], v[2:3], v[2:3] op_sel:[0,1]
	v_pk_mov_b32 v[120:121], v[2:3], v[2:3] op_sel:[0,1]
	v_pk_mov_b32 v[126:127], v[2:3], v[2:3] op_sel:[0,1]
	v_pk_mov_b32 v[128:129], v[2:3], v[2:3] op_sel:[0,1]

.LBB0_1593:
	s_ashr_i32 s19, s18, 31
	s_lshl_b64 s[0:1], s[18:19], 20
	s_add_u32 s20, s42, s0
	s_addc_u32 s21, s43, s1
	s_and_b64 s[0:1], s[8:9], exec
	s_cselect_b32 s19, s21, s5
	s_cselect_b32 s49, s20, s4
	s_ashr_i32 s17, s16, 31
	s_lshl_b64 s[0:1], s[16:17], 20
	s_add_u32 s22, s30, s0
	s_addc_u32 s23, s31, s1
	s_and_b64 s[0:1], s[8:9], exec
	s_cselect_b32 s17, s23, s3
	s_cselect_b32 s58, s22, s2
	s_add_u32 s28, s4, 0x80080
	s_addc_u32 s29, s5, 0
	s_add_u32 s59, s2, 0x100
	v_mov_b32_e32 v2, 0
	s_addc_u32 s60, s3, 0
	s_mov_b32 s61, -2
	v_mov_b32_e32 v3, v2
	s_cmp_eq_u32 s101, 0x80000001
	s_cbranch_scc0 .Lpeel_zero_10
	s_add_u32 s0, s28, 0xfff80080
	s_addc_u32 s1, s29, -1
	s_add_i32 s33, 0, 0x10000
	s_cmp_eq_u32 s61, 28
	s_cselect_b32 s5, s19, s1
	s_cselect_b32 s4, s49, s0
	s_cselect_b32 s3, s17, s60
	s_cselect_b32 s2, s58, s59
	s_add_i32 s55, 0, 0x14000
	ds_read_b128 v[146:149], v143
	ds_read_b128 v[150:153], v143 offset:1024
	ds_read_b128 v[154:157], v143 offset:2048
	ds_read_b128 v[158:161], v143 offset:3072
	ds_read_b128 v[162:165], v143 offset:16384
	ds_read_b128 v[166:169], v143 offset:17408
	ds_read_b128 v[170:173], v143 offset:18432
	ds_read_b128 v[174:177], v143 offset:19456
	s_add_i32 m0, s25, 0xc000
	ds_read_b128 v[178:181], v145
	ds_read_b128 v[182:185], v145 offset:1024
	ds_read_b128 v[186:189], v145 offset:2048
	ds_read_b128 v[190:193], v145 offset:3072
	ds_read_b128 v[194:197], v145 offset:4096
	ds_read_b128 v[198:201], v145 offset:5120
	ds_read_b128 v[208:211], v145 offset:6144
	ds_read_b128 v[212:215], v145 offset:7168
	global_load_lds_dwordx4 v136, s[28:29]
	s_add_i32 m0, s25, 0xe000
	s_nop 0
	global_load_lds_dwordx4 v138, s[28:29]
	s_waitcnt vmcnt(16)
	s_waitcnt lgkmcnt(0)
	s_setprio 1
	s_barrier
	v_mfma_f32_16x16x32_bf16 v[126:129], v[146:149], v[178:181], 0
	v_mfma_f32_16x16x32_bf16 v[118:121], v[154:157], v[178:181], 0
	v_mfma_f32_16x16x32_bf16 v[110:113], v[146:149], v[186:189], 0
	v_mfma_f32_16x16x32_bf16 v[102:105], v[154:157], v[186:189], 0
	v_mfma_f32_16x16x32_bf16 v[94:97], v[146:149], v[194:197], 0
	v_mfma_f32_16x16x32_bf16 v[86:89], v[154:157], v[194:197], 0
	v_mfma_f32_16x16x32_bf16 v[78:81], v[146:149], v[208:211], 0
	v_mfma_f32_16x16x32_bf16 v[70:73], v[154:157], v[208:211], 0
	v_mfma_f32_16x16x32_bf16 v[126:129], v[150:153], v[182:185], v[126:129]
	v_mfma_f32_16x16x32_bf16 v[118:121], v[158:161], v[182:185], v[118:121]
	v_mfma_f32_16x16x32_bf16 v[110:113], v[150:153], v[190:193], v[110:113]
	v_mfma_f32_16x16x32_bf16 v[102:105], v[158:161], v[190:193], v[102:105]
	v_mfma_f32_16x16x32_bf16 v[94:97], v[150:153], v[198:201], v[94:97]
	v_mfma_f32_16x16x32_bf16 v[86:89], v[158:161], v[198:201], v[86:89]
	v_mfma_f32_16x16x32_bf16 v[78:81], v[150:153], v[212:215], v[78:81]
	v_mfma_f32_16x16x32_bf16 v[70:73], v[158:161], v[212:215], v[70:73]
	v_mfma_f32_16x16x32_bf16 v[122:125], v[162:165], v[178:181], 0
	v_mfma_f32_16x16x32_bf16 v[114:117], v[170:173], v[178:181], 0
	v_mfma_f32_16x16x32_bf16 v[106:109], v[162:165], v[186:189], 0
	v_mfma_f32_16x16x32_bf16 v[98:101], v[170:173], v[186:189], 0
	v_mfma_f32_16x16x32_bf16 v[90:93], v[162:165], v[194:197], 0
	v_mfma_f32_16x16x32_bf16 v[82:85], v[170:173], v[194:197], 0
	v_mfma_f32_16x16x32_bf16 v[74:77], v[162:165], v[208:211], 0
	v_mfma_f32_16x16x32_bf16 v[66:69], v[170:173], v[208:211], 0
	v_mfma_f32_16x16x32_bf16 v[122:125], v[166:169], v[182:185], v[122:125]
	v_mfma_f32_16x16x32_bf16 v[114:117], v[174:177], v[182:185], v[114:117]
	v_mfma_f32_16x16x32_bf16 v[106:109], v[166:169], v[190:193], v[106:109]
	v_mfma_f32_16x16x32_bf16 v[98:101], v[174:177], v[190:193], v[98:101]
	v_mfma_f32_16x16x32_bf16 v[90:93], v[166:169], v[198:201], v[90:93]
	v_mfma_f32_16x16x32_bf16 v[82:85], v[174:177], v[198:201], v[82:85]
	v_mfma_f32_16x16x32_bf16 v[74:77], v[166:169], v[212:215], v[74:77]
	v_mfma_f32_16x16x32_bf16 v[66:69], v[174:177], v[212:215], v[66:69]
	s_barrier
	s_setprio 0
	s_add_i32 s0, s33, s36
	s_mov_b32 m0, s0
	ds_read_b128 v[178:181], v145 offset:16384
	ds_read_b128 v[182:185], v145 offset:17408
	ds_read_b128 v[186:189], v145 offset:18432
	ds_read_b128 v[190:193], v145 offset:19456
	ds_read_b128 v[194:197], v145 offset:20480
	ds_read_b128 v[198:201], v145 offset:21504
	ds_read_b128 v[208:211], v145 offset:22528
	ds_read_b128 v[212:215], v145 offset:23552
	global_load_lds_dwordx4 v202, s[2:3]
	s_add_i32 m0, s0, 0x2000
	s_add_u32 s0, s2, 0x80000
	s_addc_u32 s1, s3, 0
	s_add_i32 s33, s55, s36
	global_load_lds_dwordx4 v130, s[2:3]
	s_mov_b32 m0, s33
	s_nop 0
	global_load_lds_dwordx4 v202, s[0:1]
	s_add_i32 m0, s33, 0x2000
	s_nop 0
	global_load_lds_dwordx4 v130, s[0:1]
	s_mov_b32 m0, s25
	s_nop 0
	global_load_lds_dwordx4 v134, s[4:5]
	s_mov_b32 m0, s27
	s_nop 0
	global_load_lds_dwordx4 v132, s[4:5]
	s_waitcnt vmcnt(16)
	s_waitcnt lgkmcnt(0)
	s_setprio 1
	s_barrier
	v_mfma_f32_16x16x32_bf16 v[62:65], v[146:149], v[178:181], 0
	v_mfma_f32_16x16x32_bf16 v[54:57], v[154:157], v[178:181], 0
	v_mfma_f32_16x16x32_bf16 v[46:49], v[146:149], v[186:189], 0
	v_mfma_f32_16x16x32_bf16 v[38:41], v[154:157], v[186:189], 0
	v_mfma_f32_16x16x32_bf16 v[30:33], v[146:149], v[194:197], 0
	v_mfma_f32_16x16x32_bf16 v[22:25], v[154:157], v[194:197], 0
	v_mfma_f32_16x16x32_bf16 v[14:17], v[146:149], v[208:211], 0
	v_mfma_f32_16x16x32_bf16 v[6:9], v[154:157], v[208:211], 0
	v_mfma_f32_16x16x32_bf16 v[62:65], v[150:153], v[182:185], v[62:65]
	v_mfma_f32_16x16x32_bf16 v[54:57], v[158:161], v[182:185], v[54:57]
	v_mfma_f32_16x16x32_bf16 v[46:49], v[150:153], v[190:193], v[46:49]
	v_mfma_f32_16x16x32_bf16 v[38:41], v[158:161], v[190:193], v[38:41]
	v_mfma_f32_16x16x32_bf16 v[30:33], v[150:153], v[198:201], v[30:33]
	v_mfma_f32_16x16x32_bf16 v[22:25], v[158:161], v[198:201], v[22:25]
	v_mfma_f32_16x16x32_bf16 v[14:17], v[150:153], v[212:215], v[14:17]
	v_mfma_f32_16x16x32_bf16 v[6:9], v[158:161], v[212:215], v[6:9]
	v_mfma_f32_16x16x32_bf16 v[58:61], v[162:165], v[178:181], 0
	v_mfma_f32_16x16x32_bf16 v[50:53], v[170:173], v[178:181], 0
	v_mfma_f32_16x16x32_bf16 v[42:45], v[162:165], v[186:189], 0
	v_mfma_f32_16x16x32_bf16 v[34:37], v[170:173], v[186:189], 0
	v_mfma_f32_16x16x32_bf16 v[26:29], v[162:165], v[194:197], 0
	v_mfma_f32_16x16x32_bf16 v[18:21], v[170:173], v[194:197], 0
	v_mfma_f32_16x16x32_bf16 v[10:13], v[162:165], v[208:211], 0
	v_mfma_f32_16x16x32_bf16 v[2:5], v[170:173], v[208:211], 0
	v_mfma_f32_16x16x32_bf16 v[58:61], v[166:169], v[182:185], v[58:61]
	v_mfma_f32_16x16x32_bf16 v[50:53], v[174:177], v[182:185], v[50:53]
	v_mfma_f32_16x16x32_bf16 v[42:45], v[166:169], v[190:193], v[42:45]
	v_mfma_f32_16x16x32_bf16 v[34:37], v[174:177], v[190:193], v[34:37]
	v_mfma_f32_16x16x32_bf16 v[26:29], v[166:169], v[198:201], v[26:29]
	v_mfma_f32_16x16x32_bf16 v[18:21], v[174:177], v[198:201], v[18:21]
	v_mfma_f32_16x16x32_bf16 v[10:13], v[166:169], v[212:215], v[10:13]
	v_mfma_f32_16x16x32_bf16 v[2:5], v[174:177], v[212:215], v[2:5]
	s_barrier
	s_setprio 0
	s_branch .Lpeel_mid_10
